# code placement: 64-byte alignment of the three attention compute-block entries (back-branch targets)
# baseline (speedup 1.0000x reference)
; #define ATT_DMA2(ss) do { _Pragma("unroll") for (int hf = 0; hf < 2; ++hf) _Pragma("unroll") for (int j = 0; j < 4; ++j) if ((j * 8 + wave) * 64 < NKCH + NVCH) { \
;         __builtin_amdgcn_global_load_lds((const unsigned*)src[j], (LAS unsigned*)(lds + ((ss) * 2 + hf) * TILE + (j * 8 + wave) * 1024), 16, 0, 0); src[j] += step[j]; } } while (0)
; template <int DQK, int DV, int kpitch, int vpitch>
; DI void attn_map(LAS unsigned char* lds, const bf16x8 (&qf)[DQK / 16], const bf16* Kg, const bf16* Vg, f32x16 (&o)[DV / 32], float& lsum, int tid, int lane) {
;     ...
;     const int r = lane & 31, h = lane >> 5;
;     const int koff = r * KSTR + h * 16;
;     const int voff = KBUF + (4 * h + ((lane & 15) >> 2)) * VSTR + (((lane >> 4) & 1) * 16 + (lane & 3) * 4) * 2;
;     float l0 = 0.f, l1 = 0.f, l2 = 0.f, l3 = 0.f;
; #pragma unroll
;     for (int d = 0; d < DV / 32; ++d)
; #pragma unroll
;         for (int i = 0; i < 16; ++i) o[d][i] = 0.f;
;     asm volatile("" ::: "memory");
;     __builtin_amdgcn_s_barrier();
;     asm volatile("" ::: "memory");
;     ATT_DMA2(0);
.LBB0_1823:
	v_lshlrev_b32_e32 v196, 2, v200
	v_lshrrev_b32_e32 v2, 2, v208
	v_and_or_b32 v2, v2, 3, v196
	s_movk_i32 s10, 0x140
	v_and_b32_e32 v3, 16, v208
	v_lshlrev_b32_e32 v4, 2, v208
	v_lshlrev_b32_e32 v1, 4, v200
	v_mul_lo_u32 v2, v2, s10
	v_and_or_b32 v3, v4, 12, v3
	s_movk_i32 s10, 0x90
	v_mov_b32_e32 v169, 0
	v_mad_u32_u24 v197, v0, s10, v1
	s_lshl_b32 s22, s22, 10
	s_lshl_b32 s23, s23, 10
	s_lshl_b32 s24, s24, 10
	v_lshl_or_b32 v209, v3, 1, v2
	s_mov_b32 s26, 0
	v_mov_b32_e32 v171, 0
	v_mov_b32_e32 v168, 0
	v_mov_b32_e32 v170, 0
	v_mov_b32_e32 v0, 0
	v_mov_b32_e32 v1, v169
	v_mov_b32_e32 v2, v169
	v_mov_b32_e32 v3, v169
	v_mov_b32_e32 v4, v169
	v_mov_b32_e32 v5, v169
	v_mov_b32_e32 v6, v169
	v_mov_b32_e32 v7, v169
	v_mov_b32_e32 v8, v169
	v_mov_b32_e32 v9, v169
	v_mov_b32_e32 v10, v169
	v_mov_b32_e32 v11, v169
	v_mov_b32_e32 v12, v169
	v_mov_b32_e32 v13, v169
	v_mov_b32_e32 v14, v169
	v_mov_b32_e32 v15, v169
	v_mov_b32_e32 v16, 0
	v_mov_b32_e32 v17, v169
	v_mov_b32_e32 v18, v169
	v_mov_b32_e32 v19, v169
	v_mov_b32_e32 v20, v169
	v_mov_b32_e32 v21, v169
	v_mov_b32_e32 v22, v169
	v_mov_b32_e32 v23, v169
	v_mov_b32_e32 v24, v169
	v_mov_b32_e32 v25, v169
	v_mov_b32_e32 v26, v169
	v_mov_b32_e32 v27, v169
	v_mov_b32_e32 v28, v169
	v_mov_b32_e32 v29, v169
	v_mov_b32_e32 v30, v169
	v_mov_b32_e32 v31, v169
	v_mov_b32_e32 v32, 0
	v_mov_b32_e32 v33, v169
	v_mov_b32_e32 v34, v169
	v_mov_b32_e32 v35, v169
	v_mov_b32_e32 v36, v169
	v_mov_b32_e32 v37, v169
	v_mov_b32_e32 v38, v169
	v_mov_b32_e32 v39, v169
	v_mov_b32_e32 v40, v169
	v_mov_b32_e32 v41, v169
	v_mov_b32_e32 v42, v169
	v_mov_b32_e32 v43, v169
	v_mov_b32_e32 v44, v169
	v_mov_b32_e32 v45, v169
	v_mov_b32_e32 v46, v169
	v_mov_b32_e32 v47, v169
	v_mov_b32_e32 v48, 0
	v_mov_b32_e32 v49, v169
	v_mov_b32_e32 v50, v169
	v_mov_b32_e32 v51, v169
	v_mov_b32_e32 v52, v169
	v_mov_b32_e32 v53, v169
	v_mov_b32_e32 v54, v169
	v_mov_b32_e32 v55, v169
	v_mov_b32_e32 v56, v169
	v_mov_b32_e32 v57, v169
	v_mov_b32_e32 v58, v169
	v_mov_b32_e32 v59, v169
	v_mov_b32_e32 v60, v169
	v_mov_b32_e32 v61, v169
	v_mov_b32_e32 v62, v169
	v_mov_b32_e32 v63, v169
	s_waitcnt vmcnt(0)
	v_readfirstlane_b32 s86, v64
	v_readfirstlane_b32 s87, v65
	s_nop 0
	s_sub_u32 s86, s86, 0x100
	s_subb_u32 s87, s87, 0
	v_subrev_u32_e32 v128, s86, v64
	v_subrev_u32_e32 v130, s86, v66
	v_subrev_u32_e32 v132, s86, v68
	v_subrev_u32_e32 v134, s86, v70
	s_branch .LBB0_1825
	.p2align 6

; #define ATT_DMA2(ss) do { _Pragma("unroll") for (int hf = 0; hf < 2; ++hf) _Pragma("unroll") for (int j = 0; j < 4; ++j) if ((j * 8 + wave) * 64 < NKCH + NVCH) { \
;         __builtin_amdgcn_global_load_lds((const unsigned*)src[j], (LAS unsigned*)(lds + ((ss) * 2 + hf) * TILE + (j * 8 + wave) * 1024), 16, 0, 0); src[j] += step[j]; } } while (0)
; template <int DQK, int DV, int kpitch, int vpitch>
; DI void attn_map(LAS unsigned char* lds, const bf16x8 (&qf)[DQK / 16], const bf16* Kg, const bf16* Vg, f32x16 (&o)[DV / 32], float& lsum, int tid, int lane) {
;     ...
;     float l0 = 0.f, l1 = 0.f, l2 = 0.f, l3 = 0.f;
; #pragma unroll
;     for (int d = 0; d < DV / 32; ++d)
; #pragma unroll
;         for (int i = 0; i < 16; ++i) o[d][i] = 0.f;
;     asm volatile("" ::: "memory");
;     __builtin_amdgcn_s_barrier();
;     asm volatile("" ::: "memory");
;     ATT_DMA2(0);
.LBB0_1887:
	v_mov_b32_e32 v169, 0
	s_lshl_b32 s22, s22, 10
	s_lshl_b32 s23, s23, 10
	s_lshl_b32 s24, s24, 10
	s_mov_b32 s26, 0
	v_mov_b32_e32 v171, 0
	v_mov_b32_e32 v168, 0
	v_mov_b32_e32 v170, 0
	v_mov_b32_e32 v16, 0
	v_mov_b32_e32 v17, v169
	v_mov_b32_e32 v18, v169
	v_mov_b32_e32 v19, v169
	v_mov_b32_e32 v20, v169
	v_mov_b32_e32 v21, v169
	v_mov_b32_e32 v22, v169
	v_mov_b32_e32 v23, v169
	v_mov_b32_e32 v24, v169
	v_mov_b32_e32 v25, v169
	v_mov_b32_e32 v26, v169
	v_mov_b32_e32 v27, v169
	v_mov_b32_e32 v28, v169
	v_mov_b32_e32 v29, v169
	v_mov_b32_e32 v30, v169
	v_mov_b32_e32 v31, v169
	v_mov_b32_e32 v32, 0
	v_mov_b32_e32 v33, v169
	v_mov_b32_e32 v34, v169
	v_mov_b32_e32 v35, v169
	v_mov_b32_e32 v36, v169
	v_mov_b32_e32 v37, v169
	v_mov_b32_e32 v38, v169
	v_mov_b32_e32 v39, v169
	v_mov_b32_e32 v40, v169
	v_mov_b32_e32 v41, v169
	v_mov_b32_e32 v42, v169
	v_mov_b32_e32 v43, v169
	v_mov_b32_e32 v44, v169
	v_mov_b32_e32 v45, v169
	v_mov_b32_e32 v46, v169
	v_mov_b32_e32 v47, v169
	v_mov_b32_e32 v48, 0
	v_mov_b32_e32 v49, v169
	v_mov_b32_e32 v50, v169
	v_mov_b32_e32 v51, v169
	v_mov_b32_e32 v52, v169
	v_mov_b32_e32 v53, v169
	v_mov_b32_e32 v54, v169
	v_mov_b32_e32 v55, v169
	v_mov_b32_e32 v56, v169
	v_mov_b32_e32 v57, v169
	v_mov_b32_e32 v58, v169
	v_mov_b32_e32 v59, v169
	v_mov_b32_e32 v60, v169
	v_mov_b32_e32 v61, v169
	v_mov_b32_e32 v62, v169
	v_mov_b32_e32 v63, v169
	v_mov_b32_e32 v0, 0
	v_mov_b32_e32 v1, v169
	v_mov_b32_e32 v2, v169
	v_mov_b32_e32 v3, v169
	v_mov_b32_e32 v4, v169
	v_mov_b32_e32 v5, v169
	v_mov_b32_e32 v6, v169
	v_mov_b32_e32 v7, v169
	v_mov_b32_e32 v8, v169
	v_mov_b32_e32 v9, v169
	v_mov_b32_e32 v10, v169
	v_mov_b32_e32 v11, v169
	v_mov_b32_e32 v12, v169
	v_mov_b32_e32 v13, v169
	v_mov_b32_e32 v14, v169
	v_mov_b32_e32 v15, v169
	s_waitcnt vmcnt(0)
	v_readfirstlane_b32 s86, v64
	v_readfirstlane_b32 s87, v65
	s_nop 0
	s_sub_u32 s86, s86, 0x100
	s_subb_u32 s87, s87, 0
	v_subrev_u32_e32 v128, s86, v64
	v_subrev_u32_e32 v130, s86, v66
	v_subrev_u32_e32 v132, s86, v68
	v_subrev_u32_e32 v134, s86, v70
	s_branch .LBB0_1889
	.p2align 6

; DI unsigned cvtpk(float lo, float hi) { f32x2 v = {lo, hi}; bf16x2_t b = __builtin_convertvector(v, bf16x2_t); return __builtin_bit_cast(unsigned, b); }
; template <int DQK, int DV, int kpitch, int vpitch>
; DI void attn_map(LAS unsigned char* lds, const bf16x8 (&qf)[DQK / 16], const bf16* Kg, const bf16* Vg, f32x16 (&o)[DV / 32], float& lsum, int tid, int lane) {
;     ...
;     float l0 = 0.f, l1 = 0.f, l2 = 0.f, l3 = 0.f;
; #pragma unroll
;     for (int d = 0; d < DV / 32; ++d)
; #pragma unroll
;         for (int i = 0; i < 16; ++i) o[d][i] = 0.f;
; DI void mla_unit(const Params& p, LAS unsigned char* lds, int b, int head, int qb, int tid, int lane, int wave) {
;     ...
;     const float sq = rsqrtf((QSSN[row * 8 + head] + QSSP[row * 8 + head]) * (1.f / 96.f) + EPS) * (LOG2E * 0.10206207261596575f);
;     bf16x8 qf[6];
; #pragma unroll
;     for (int ks = 0; ks < 6; ++ks) { const bf16x8 raw = *(const bf16x8*)(QM + row * 768 + head * 96 + ks * 16 + h * 8); u32x4 w;
;         w.x = cvtpk(bf2f(raw[0]) * sq, bf2f(raw[1]) * sq); w.y = cvtpk(bf2f(raw[2]) * sq, bf2f(raw[3]) * sq); w.z = cvtpk(bf2f(raw[4]) * sq, bf2f(raw[5]) * sq); w.w = cvtpk(bf2f(raw[6]) * sq, bf2f(raw[7]) * sq);
;         qf[ks] = __builtin_bit_cast(bf16x8, w); }
.LBB0_1951:
	s_waitcnt vmcnt(6)
	v_add_f32_e32 v26, v26, v27
	v_fmamk_f32 v26, v26, 0x3c2aaaab, v232
	v_mul_f32_e32 v27, 0x4b800000, v26
	v_cmp_gt_f32_e32 vcc, s74, v26
	v_bfe_u32 v28, v150, 2, 2
	v_lshlrev_b32_e32 v30, 4, v25
	v_cndmask_b32_e32 v26, v26, v27, vcc
	v_rsq_f32_e32 v26, v26
	v_lshl_or_b32 v25, v25, 2, v28
	v_and_b32_e32 v27, 16, v150
	v_lshlrev_b32_e32 v28, 2, v150
	v_and_or_b32 v27, v28, 12, v27
	v_mul_f32_e32 v28, 0x45800000, v26
	v_cndmask_b32_e32 v26, v26, v28, vcc
	v_mul_f32_e32 v26, 0x3e16c740, v26
	v_and_b32_e32 v29, 0xffff0000, v20
	v_lshlrev_b32_e32 v28, 16, v20
	v_pk_mul_f32 v[28:29], v[26:27], v[28:29] op_sel_hi:[0,1]
	v_cvt_pk_bf16_f32 v104, v28, v29
	v_and_b32_e32 v29, 0xffff0000, v21
	v_lshlrev_b32_e32 v28, 16, v21
	v_pk_mul_f32 v[20:21], v[26:27], v[28:29] op_sel_hi:[0,1]
	v_cvt_pk_bf16_f32 v105, v20, v21
	v_and_b32_e32 v21, 0xffff0000, v22
	v_lshlrev_b32_e32 v20, 16, v22
	v_pk_mul_f32 v[20:21], v[26:27], v[20:21] op_sel_hi:[0,1]
	v_cvt_pk_bf16_f32 v106, v20, v21
	v_and_b32_e32 v21, 0xffff0000, v23
	v_lshlrev_b32_e32 v20, 16, v23
	v_pk_mul_f32 v[20:21], v[26:27], v[20:21] op_sel_hi:[0,1]
	v_cvt_pk_bf16_f32 v107, v20, v21
	v_and_b32_e32 v21, 0xffff0000, v16
	v_lshlrev_b32_e32 v20, 16, v16
	v_pk_mul_f32 v[20:21], v[26:27], v[20:21] op_sel_hi:[0,1]
	v_cvt_pk_bf16_f32 v108, v20, v21
	v_and_b32_e32 v21, 0xffff0000, v17
	v_lshlrev_b32_e32 v20, 16, v17
	v_pk_mul_f32 v[16:17], v[26:27], v[20:21] op_sel_hi:[0,1]
	v_cvt_pk_bf16_f32 v109, v16, v17
	v_and_b32_e32 v17, 0xffff0000, v18
	v_lshlrev_b32_e32 v16, 16, v18
	v_pk_mul_f32 v[16:17], v[26:27], v[16:17] op_sel_hi:[0,1]
	v_cvt_pk_bf16_f32 v110, v16, v17
	v_and_b32_e32 v17, 0xffff0000, v19
	v_lshlrev_b32_e32 v16, 16, v19
	v_pk_mul_f32 v[16:17], v[26:27], v[16:17] op_sel_hi:[0,1]
	v_cvt_pk_bf16_f32 v111, v16, v17
	v_and_b32_e32 v17, 0xffff0000, v12
	v_lshlrev_b32_e32 v16, 16, v12
	v_pk_mul_f32 v[16:17], v[26:27], v[16:17] op_sel_hi:[0,1]
	v_cvt_pk_bf16_f32 v112, v16, v17
	v_and_b32_e32 v17, 0xffff0000, v13
	v_lshlrev_b32_e32 v16, 16, v13
	v_pk_mul_f32 v[12:13], v[26:27], v[16:17] op_sel_hi:[0,1]
	v_cvt_pk_bf16_f32 v113, v12, v13
	v_and_b32_e32 v13, 0xffff0000, v14
	v_lshlrev_b32_e32 v12, 16, v14
	v_pk_mul_f32 v[12:13], v[26:27], v[12:13] op_sel_hi:[0,1]
	v_cvt_pk_bf16_f32 v114, v12, v13
	v_and_b32_e32 v13, 0xffff0000, v15
	v_lshlrev_b32_e32 v12, 16, v15
	v_pk_mul_f32 v[12:13], v[26:27], v[12:13] op_sel_hi:[0,1]
	v_cvt_pk_bf16_f32 v115, v12, v13
	v_and_b32_e32 v13, 0xffff0000, v8
	v_lshlrev_b32_e32 v12, 16, v8
	v_pk_mul_f32 v[12:13], v[26:27], v[12:13] op_sel_hi:[0,1]
	v_cvt_pk_bf16_f32 v116, v12, v13
	v_and_b32_e32 v13, 0xffff0000, v9
	v_lshlrev_b32_e32 v12, 16, v9
	v_pk_mul_f32 v[8:9], v[26:27], v[12:13] op_sel_hi:[0,1]
	v_cvt_pk_bf16_f32 v117, v8, v9
	v_and_b32_e32 v9, 0xffff0000, v10
	v_lshlrev_b32_e32 v8, 16, v10
	v_pk_mul_f32 v[8:9], v[26:27], v[8:9] op_sel_hi:[0,1]
	v_cvt_pk_bf16_f32 v118, v8, v9
	v_and_b32_e32 v9, 0xffff0000, v11
	v_lshlrev_b32_e32 v8, 16, v11
	v_pk_mul_f32 v[8:9], v[26:27], v[8:9] op_sel_hi:[0,1]
	v_cvt_pk_bf16_f32 v119, v8, v9
	v_and_b32_e32 v9, 0xffff0000, v4
	v_lshlrev_b32_e32 v8, 16, v4
	v_pk_mul_f32 v[8:9], v[26:27], v[8:9] op_sel_hi:[0,1]
	v_cvt_pk_bf16_f32 v120, v8, v9
	v_and_b32_e32 v9, 0xffff0000, v5
	v_lshlrev_b32_e32 v8, 16, v5
	v_pk_mul_f32 v[4:5], v[26:27], v[8:9] op_sel_hi:[0,1]
	v_cvt_pk_bf16_f32 v121, v4, v5
	v_and_b32_e32 v5, 0xffff0000, v6
	v_lshlrev_b32_e32 v4, 16, v6
	v_pk_mul_f32 v[4:5], v[26:27], v[4:5] op_sel_hi:[0,1]
	v_cvt_pk_bf16_f32 v122, v4, v5
	v_and_b32_e32 v5, 0xffff0000, v7
	v_lshlrev_b32_e32 v4, 16, v7
	v_pk_mul_f32 v[4:5], v[26:27], v[4:5] op_sel_hi:[0,1]
	v_cvt_pk_bf16_f32 v123, v4, v5
	v_and_b32_e32 v5, 0xffff0000, v0
	v_lshlrev_b32_e32 v4, 16, v0
	v_pk_mul_f32 v[4:5], v[26:27], v[4:5] op_sel_hi:[0,1]
	v_cvt_pk_bf16_f32 v124, v4, v5
	v_and_b32_e32 v5, 0xffff0000, v1
	v_lshlrev_b32_e32 v4, 16, v1
	v_pk_mul_f32 v[0:1], v[26:27], v[4:5] op_sel_hi:[0,1]
	v_cvt_pk_bf16_f32 v125, v0, v1
	v_and_b32_e32 v1, 0xffff0000, v2
	v_lshlrev_b32_e32 v0, 16, v2
	v_pk_mul_f32 v[0:1], v[26:27], v[0:1] op_sel_hi:[0,1]
	s_movk_i32 s10, 0xc0
	v_cvt_pk_bf16_f32 v126, v0, v1
	v_and_b32_e32 v1, 0xffff0000, v3
	v_lshlrev_b32_e32 v0, 16, v3
	v_mul_lo_u32 v25, v25, s10
	v_pk_mul_f32 v[0:1], v[26:27], v[0:1] op_sel_hi:[0,1]
	s_movk_i32 s10, 0xd0
	v_mov_b32_e32 v147, 0
	s_lshl_b32 s13, s13, 6
	v_cvt_pk_bf16_f32 v127, v0, v1
	v_mad_u32_u24 v151, v24, s10, v30
	s_lshl_b32 s23, s23, 10
	s_lshl_b32 s24, s24, 10
	s_lshl_b32 s25, s25, 10
	v_lshl_or_b32 v152, v27, 1, v25
	s_mov_b32 s27, 0
	v_mov_b32_e32 v149, 0
	v_mov_b32_e32 v146, 0
	v_mov_b32_e32 v148, 0
	v_mov_b32_e32 v16, 0
	v_mov_b32_e32 v17, v147
	v_mov_b32_e32 v18, v147
	v_mov_b32_e32 v19, v147
	v_mov_b32_e32 v20, v147
	v_mov_b32_e32 v21, v147
	v_mov_b32_e32 v22, v147
	v_mov_b32_e32 v23, v147
	v_mov_b32_e32 v24, v147
	v_mov_b32_e32 v25, v147
	v_mov_b32_e32 v26, v147
	v_mov_b32_e32 v27, v147
	v_mov_b32_e32 v28, v147
	v_mov_b32_e32 v29, v147
	v_mov_b32_e32 v30, v147
	v_mov_b32_e32 v31, v147
	v_mov_b32_e32 v0, 0
	v_mov_b32_e32 v1, v147
	v_mov_b32_e32 v2, v147
	v_mov_b32_e32 v3, v147
	v_mov_b32_e32 v4, v147
	v_mov_b32_e32 v5, v147
	v_mov_b32_e32 v6, v147
	v_mov_b32_e32 v7, v147
	v_mov_b32_e32 v8, v147
	v_mov_b32_e32 v9, v147
	v_mov_b32_e32 v10, v147
	v_mov_b32_e32 v11, v147
	v_mov_b32_e32 v12, v147
	v_mov_b32_e32 v13, v147
	v_mov_b32_e32 v14, v147
	v_mov_b32_e32 v15, v147
	s_branch .LBB0_1953
	.p2align 6
